# mlstm_a state stores regrouped through a wave-private LDS patch into two 16-byte stores per lane (was 16 two-byte stores), on top of the load hoists
# speedup vs baseline: 1.0100x; 1.0075x over previous
; __device__ __forceinline__ bf16_t f2bf(float f) { return (bf16_t)(cvt_pk_bf16(f, 0.f) & 0xffffu); }
; __device__ __forceinline__ bf16_t f2bf_sw(float f) { const unsigned u = __float_as_uint(f); return (bf16_t)((u + 0x7fffu + ((u >> 16) & 1u)) >> 16); }
; __device__ __forceinline__ void phase_mlstm_a(const Args& a, unsigned char* lds) {
;     ...
;             for (int e = 0; e < 8; ++e) VT[(d0 + e) * 72 + s] = f2bf(f[e]); }
;         __syncthreads();
;         { const int s = tid >> 3, d0 = (tid & 7) * 8; float f[8]; unpack8(*(const u32x4*)(QK + (r0 + s) * 512 + 256 + h * 64 + d0), f); const float w = WS_[s];
; #pragma unroll
;             for (int e = 0; e < 8; ++e) KT[(d0 + e) * 72 + s] = f2bf(f[e] * w); }
;         __syncthreads();
;         bf16_t* st = ST + (size_t)item * 8192;
; #pragma unroll
;         for (int nt = 0; nt < 4; ++nt) {
;             const f32x4 acc = mma_lds(VT + wave * 16 * 72, 72, KT + nt * 16 * 72, 72, 64, lane);
; #pragma unroll
;             for (int j = 0; j < 4; ++j) st[(wave * 16 + (lane >> 4) * 4 + j) * 64 + nt * 16 + (lane & 15)] = f2bf_sw(acc[j]);
;         }
.LBB0_659:
	s_or_b64 exec, exec, s[20:21]
	v_and_b32_e32 v39, 0x78, v162
	v_mad_u32_u24 v39, v39, s26, v12
	s_waitcnt vmcnt(2)
	ds_write_b16 v39, v228
	ds_write_b16_d16_hi v39, v228 offset:144
	ds_write_b16 v39, v229 offset:288
	ds_write_b16_d16_hi v39, v229 offset:432
	ds_write_b16 v39, v230 offset:576
	ds_write_b16_d16_hi v39, v230 offset:720
	ds_write_b16 v39, v231 offset:864
	ds_write_b16_d16_hi v39, v231 offset:1008
	s_waitcnt vmcnt(1)
	ds_write_b16 v39, v232 offset:64
	ds_write_b16_d16_hi v39, v232 offset:208
	ds_write_b16 v39, v233 offset:352
	ds_write_b16_d16_hi v39, v233 offset:496
	ds_write_b16 v39, v234 offset:640
	ds_write_b16_d16_hi v39, v234 offset:784
	ds_write_b16 v39, v235 offset:928
	ds_write_b16_d16_hi v39, v235 offset:1072
	s_waitcnt lgkmcnt(0)
	s_barrier
	ds_read_b32 v0, v7 offset:27648
	s_ashr_i32 s15, s14, 31
	s_lshl_b64 s[16:17], s[14:15], 14
	s_add_u32 s16, s46, s16
	s_addc_u32 s17, s47, s17
	s_waitcnt vmcnt(0)
	v_mov_b32_e32 v38, v236
	v_mov_b32_e32 v39, v237
	v_mov_b32_e32 v40, v238
	v_mov_b32_e32 v41, v239
	v_lshlrev_b32_e32 v4, 16, v38
	s_waitcnt lgkmcnt(0)
	v_mul_f32_e32 v4, v0, v4
	v_and_b32_e32 v5, 0xffff0000, v38
	v_cvt_pk_bf16_f32 v4, v4, v1
	v_lshlrev_b32_e32 v37, 16, v39
	v_mul_f32_e32 v5, v0, v5
	ds_write_b16 v23, v4 offset:18432
	v_cvt_pk_bf16_f32 v4, v5, v1
	v_and_b32_e32 v38, 0xffff0000, v39
	v_mul_f32_e32 v37, v0, v37
	ds_write_b16 v23, v4 offset:18576
	v_cvt_pk_bf16_f32 v4, v37, v1
	v_lshlrev_b32_e32 v39, 16, v40
	v_mul_f32_e32 v38, v0, v38
	ds_write_b16 v23, v4 offset:18720
	v_cvt_pk_bf16_f32 v4, v38, v1
	v_and_b32_e32 v40, 0xffff0000, v40
	v_lshlrev_b32_e32 v42, 16, v41
	v_and_b32_e32 v41, 0xffff0000, v41
	v_mul_f32_e32 v39, v0, v39
	ds_write_b16 v23, v4 offset:18864
	v_cvt_pk_bf16_f32 v4, v39, v1
	v_mul_f32_e32 v40, v0, v40
	v_mul_f32_e32 v42, v0, v42
	v_mul_f32_e32 v0, v0, v41
	ds_write_b16 v23, v4 offset:19008
	v_cvt_pk_bf16_f32 v4, v40, v1
	ds_write_b16 v23, v4 offset:19152
	v_cvt_pk_bf16_f32 v4, v42, v1
	ds_write_b16 v23, v4 offset:19296
	v_cvt_pk_bf16_f32 v0, v0, v1
	ds_write_b16 v23, v0 offset:19440
	s_waitcnt lgkmcnt(0)
	s_barrier
	ds_read_b128 v[38:41], v9
	ds_read_b128 v[42:45], v8 offset:18432
	ds_read_b128 v[46:49], v9 offset:64
	ds_read_b128 v[50:53], v8 offset:18496
	ds_read_b128 v[54:57], v8 offset:20736
	ds_read_b128 v[58:61], v8 offset:20800
	ds_read_b128 v[62:65], v8 offset:23040
	ds_read_b128 v[66:69], v8 offset:23104
	ds_read_b128 v[70:73], v8 offset:25344
	ds_read_b128 v[74:77], v8 offset:25408
	s_waitcnt lgkmcnt(8)
	v_mfma_f32_16x16x32_bf16 v[42:45], v[38:41], v[42:45], 0
	s_waitcnt lgkmcnt(5)
	v_mfma_f32_16x16x32_bf16 v[54:57], v[38:41], v[54:57], 0
	s_waitcnt lgkmcnt(3)
	v_mfma_f32_16x16x32_bf16 v[62:65], v[38:41], v[62:65], 0
	s_waitcnt lgkmcnt(1)
	v_mfma_f32_16x16x32_bf16 v[38:41], v[38:41], v[70:73], 0
	v_mfma_f32_16x16x32_bf16 v[42:45], v[46:49], v[50:53], v[42:45]
	v_mfma_f32_16x16x32_bf16 v[50:53], v[46:49], v[58:61], v[54:57]
	v_mfma_f32_16x16x32_bf16 v[54:57], v[46:49], v[66:69], v[62:65]
	s_nop 5
	v_bfe_u32 v0, v42, 16, 1
	v_bfe_u32 v4, v43, 16, 1
	v_bfe_u32 v5, v44, 16, 1
	s_waitcnt lgkmcnt(0)
	v_mfma_f32_16x16x32_bf16 v[38:41], v[46:49], v[74:77], v[38:41]
	v_bfe_u32 v37, v45, 16, 1
	v_bfe_u32 v46, v50, 16, 1
	v_bfe_u32 v47, v51, 16, 1
	v_bfe_u32 v48, v52, 16, 1
	v_bfe_u32 v49, v53, 16, 1
	v_bfe_u32 v58, v54, 16, 1
	v_bfe_u32 v59, v55, 16, 1
	v_bfe_u32 v60, v56, 16, 1
	v_bfe_u32 v61, v57, 16, 1
	v_bfe_u32 v62, v38, 16, 1
	v_bfe_u32 v63, v39, 16, 1
	v_bfe_u32 v64, v40, 16, 1
	v_add3_u32 v0, v42, v0, s43
	v_add3_u32 v4, v43, v4, s43
	v_add3_u32 v5, v44, v5, s43
	v_add3_u32 v37, v45, v37, s43
	v_add3_u32 v42, v50, v46, s43
	v_add3_u32 v43, v51, v47, s43
	v_add3_u32 v44, v52, v48, s43
	v_add3_u32 v45, v53, v49, s43
	v_add3_u32 v46, v54, v58, s43
	v_add3_u32 v47, v55, v59, s43
	v_add3_u32 v48, v56, v60, s43
	v_add3_u32 v49, v57, v61, s43
	v_add3_u32 v38, v38, v62, s43
	v_add3_u32 v39, v39, v63, s43
	ds_write_b16_d16_hi v24, v0 offset:32768
	ds_write_b16_d16_hi v24, v4 offset:32896
	ds_write_b16_d16_hi v24, v5 offset:33024
	ds_write_b16_d16_hi v24, v37 offset:33152
	ds_write_b16_d16_hi v24, v42 offset:32800
	ds_write_b16_d16_hi v24, v43 offset:32928
	ds_write_b16_d16_hi v24, v44 offset:33056
	ds_write_b16_d16_hi v24, v45 offset:33184
	ds_write_b16_d16_hi v24, v46 offset:32832
	ds_write_b16_d16_hi v24, v47 offset:32960
	ds_write_b16_d16_hi v24, v48 offset:33088
	ds_write_b16_d16_hi v24, v49 offset:33216
	ds_write_b16_d16_hi v24, v38 offset:32864
	ds_write_b16_d16_hi v24, v39 offset:32992
	v_add3_u32 v0, v40, v64, s43
	ds_write_b16_d16_hi v24, v0 offset:33120
	v_bfe_u32 v0, v41, 16, 1
	v_add3_u32 v0, v41, v0, s43
	ds_write_b16_d16_hi v24, v0 offset:33248
	v_and_b32_e32 v90, 63, v156
	v_lshrrev_b32_e32 v91, 6, v156
	v_lshlrev_b32_e32 v90, 4, v90
	v_lshl_add_u32 v90, v91, 11, v90
	ds_read_b128 v[92:95], v90 offset:32768
	ds_read_b128 v[96:99], v90 offset:33792
	s_waitcnt lgkmcnt(0)
	global_store_dwordx4 v90, v[92:95], s[16:17]
	global_store_dwordx4 v90, v[96:99], s[16:17] offset:1024
	s_and_saveexec_b64 s[16:17], s[4:5]
	s_cbranch_execz .LBB0_655
; __device__ __forceinline__ float bf1(bf16_t u) { return __uint_as_float(((unsigned)u) << 16); }
; __device__ __forceinline__ void phase_mlstm_a(const Args& a, unsigned char* lds) {
;     ...
;         if (tid < 64) { float s = 0.f; for (int k = 0; k < 64; ++k) s += bf1(KT[tid * 72 + k]); DN[item * 64 + tid] = s; }
	ds_read_b128 v[38:41], v10 offset:18432
	ds_read_b128 v[42:45], v10 offset:18448
	ds_read_b128 v[46:49], v10 offset:18464
	ds_read_b128 v[50:53], v10 offset:18480
	s_waitcnt lgkmcnt(3)
	v_lshlrev_b32_e32 v0, 16, v38
	v_and_b32_e32 v4, 0xffff0000, v38
	v_add_f32_e32 v0, 0, v0
	v_add_f32_e32 v0, v0, v4
	v_lshlrev_b32_e32 v4, 16, v39
	v_add_f32_e32 v0, v0, v4
	v_and_b32_e32 v4, 0xffff0000, v39
	v_add_f32_e32 v0, v0, v4
	v_lshlrev_b32_e32 v4, 16, v40
	v_add_f32_e32 v0, v0, v4
	v_and_b32_e32 v4, 0xffff0000, v40
	v_add_f32_e32 v0, v0, v4
	v_lshlrev_b32_e32 v4, 16, v41
	v_add_f32_e32 v0, v0, v4
	v_and_b32_e32 v4, 0xffff0000, v41
	v_add_f32_e32 v0, v0, v4
	s_waitcnt lgkmcnt(2)
	v_lshlrev_b32_e32 v4, 16, v42
	v_add_f32_e32 v0, v0, v4
	v_and_b32_e32 v4, 0xffff0000, v42
	v_add_f32_e32 v0, v0, v4
	v_lshlrev_b32_e32 v4, 16, v43
	v_add_f32_e32 v0, v0, v4
	v_and_b32_e32 v4, 0xffff0000, v43
	v_add_f32_e32 v0, v0, v4
	v_lshlrev_b32_e32 v4, 16, v44
	v_add_f32_e32 v0, v0, v4
	v_and_b32_e32 v4, 0xffff0000, v44
	v_add_f32_e32 v0, v0, v4
	v_lshlrev_b32_e32 v4, 16, v45
	v_add_f32_e32 v0, v0, v4
	v_and_b32_e32 v4, 0xffff0000, v45
	v_add_f32_e32 v0, v0, v4
	s_waitcnt lgkmcnt(1)
	v_lshlrev_b32_e32 v4, 16, v46
	v_add_f32_e32 v0, v0, v4
	v_and_b32_e32 v4, 0xffff0000, v46
	v_add_f32_e32 v0, v0, v4
	v_lshlrev_b32_e32 v4, 16, v47
	v_add_f32_e32 v0, v0, v4
	v_and_b32_e32 v4, 0xffff0000, v47
	v_add_f32_e32 v0, v0, v4
	v_lshlrev_b32_e32 v4, 16, v48
	v_add_f32_e32 v0, v0, v4
	v_and_b32_e32 v4, 0xffff0000, v48
	v_add_f32_e32 v0, v0, v4
	v_lshlrev_b32_e32 v4, 16, v49
	v_add_f32_e32 v0, v0, v4
	v_and_b32_e32 v4, 0xffff0000, v49
	v_add_f32_e32 v0, v0, v4
	s_waitcnt lgkmcnt(0)
	v_lshlrev_b32_e32 v4, 16, v50
	v_add_f32_e32 v0, v0, v4
	v_and_b32_e32 v4, 0xffff0000, v50
	v_add_f32_e32 v0, v0, v4
	v_lshlrev_b32_e32 v4, 16, v51
	v_add_f32_e32 v0, v0, v4
	v_and_b32_e32 v4, 0xffff0000, v51
	ds_read_b128 v[38:41], v10 offset:18496
	ds_read_b128 v[42:45], v10 offset:18512
	v_add_f32_e32 v0, v0, v4
	v_lshlrev_b32_e32 v4, 16, v52
	v_add_f32_e32 v0, v0, v4
	v_and_b32_e32 v4, 0xffff0000, v52
	v_add_f32_e32 v0, v0, v4
	v_lshlrev_b32_e32 v4, 16, v53
	v_add_f32_e32 v0, v0, v4
	v_and_b32_e32 v4, 0xffff0000, v53
	v_add_f32_e32 v0, v0, v4
	s_waitcnt lgkmcnt(1)
	v_lshlrev_b32_e32 v4, 16, v38
	v_add_f32_e32 v0, v0, v4
	v_and_b32_e32 v4, 0xffff0000, v38
	v_add_f32_e32 v0, v0, v4
	v_lshlrev_b32_e32 v4, 16, v39
	v_add_f32_e32 v0, v0, v4
	v_and_b32_e32 v4, 0xffff0000, v39
	v_add_f32_e32 v0, v0, v4
	v_lshlrev_b32_e32 v4, 16, v40
	v_add_f32_e32 v0, v0, v4
	v_and_b32_e32 v4, 0xffff0000, v40
	v_add_f32_e32 v0, v0, v4
	v_lshlrev_b32_e32 v4, 16, v41
	v_add_f32_e32 v0, v0, v4
	v_and_b32_e32 v4, 0xffff0000, v41
	v_add_f32_e32 v0, v0, v4
	s_waitcnt lgkmcnt(0)
	v_lshlrev_b32_e32 v4, 16, v42
	v_add_f32_e32 v0, v0, v4
	v_and_b32_e32 v4, 0xffff0000, v42
	v_add_f32_e32 v0, v0, v4
	v_lshlrev_b32_e32 v4, 16, v43
	v_add_f32_e32 v0, v0, v4
	v_and_b32_e32 v4, 0xffff0000, v43
	ds_read_b128 v[38:41], v10 offset:18528
	v_add_f32_e32 v0, v0, v4
	v_lshlrev_b32_e32 v4, 16, v44
	v_add_f32_e32 v0, v0, v4
	v_and_b32_e32 v4, 0xffff0000, v44
	v_add_f32_e32 v0, v0, v4
	v_lshlrev_b32_e32 v4, 16, v45
	v_add_f32_e32 v0, v0, v4
	v_and_b32_e32 v4, 0xffff0000, v45
	v_add_f32_e32 v0, v0, v4
	ds_read_b128 v[42:45], v10 offset:18544
	s_waitcnt lgkmcnt(1)
	v_lshlrev_b32_e32 v4, 16, v38
	v_add_f32_e32 v0, v0, v4
	v_and_b32_e32 v4, 0xffff0000, v38
	v_add_f32_e32 v0, v0, v4
	v_lshlrev_b32_e32 v4, 16, v39
	v_add_f32_e32 v0, v0, v4
	v_and_b32_e32 v4, 0xffff0000, v39
	v_add_f32_e32 v0, v0, v4
	v_lshlrev_b32_e32 v4, 16, v40
	v_add_f32_e32 v0, v0, v4
	v_and_b32_e32 v4, 0xffff0000, v40
	v_add_f32_e32 v0, v0, v4
	v_lshlrev_b32_e32 v4, 16, v41
	v_add_f32_e32 v0, v0, v4
	v_and_b32_e32 v4, 0xffff0000, v41
	v_add_f32_e32 v0, v0, v4
	s_waitcnt lgkmcnt(0)
	v_lshlrev_b32_e32 v4, 16, v42
	v_add_f32_e32 v0, v0, v4
	v_and_b32_e32 v4, 0xffff0000, v42
	v_add_f32_e32 v0, v0, v4
	v_lshlrev_b32_e32 v4, 16, v43
	v_add_f32_e32 v0, v0, v4
	v_and_b32_e32 v4, 0xffff0000, v43
	v_add_f32_e32 v0, v0, v4
	v_lshlrev_b32_e32 v4, 16, v44
	v_add_f32_e32 v0, v0, v4
	v_and_b32_e32 v4, 0xffff0000, v44
	v_add_f32_e32 v0, v0, v4
	v_lshlrev_b32_e32 v4, 16, v45
	v_add_f32_e32 v0, v0, v4
	v_and_b32_e32 v4, 0xffff0000, v45
	v_add_f32_e32 v0, v0, v4
	v_or_b32_e32 v4, s60, v156
	v_ashrrev_i32_e32 v5, 31, v4
	v_lshl_add_u64 v[4:5], v[4:5], 2, s[36:37]
	global_store_dword v[4:5], v0, off
	s_branch .LBB0_655
